# dense attention loop: 14 redundant VALU per 2 KV tiles (NaN-canonicalising self-max ops in the row-max chain, 0+x row-sum inits) folded away, slots kept as s_nop
# baseline (speedup 1.0000x reference)
; #define SBAR() __builtin_amdgcn_sched_barrier(0)
; #define SLOAD(i, k0) do { sr_[i].vs0 = St::ld8(&Vh[(long)((k0) + sr) * LDK + sc]); sr_[i].vs1 = St::ld8(&Vh[(long)((k0) + 32 + sr) * LDK + sc]); \
;     sr_[i].ks0 = St::ld8(&Kh[(long)((k0) + sr) * LDK + sc]); sr_[i].ks1 = St::ld8(&Kh[(long)((k0) + 32 + sr) * LDK + sc]); } while (0)
; __device__ __forceinline__ void finishSM(f32x16& p0, f32x16& p1, float alpha, float& l_reg, bf16x8& pa0, bf16x8& pa1, bf16x8& pa2, bf16x8& pa3) {
;   for (int r = 0; r < 16; ++r) p1[r] = __builtin_amdgcn_exp2f(p1[r]);
;   float ps = 0; for (int r = 0; r < 16; ++r) ps += p0[r]; for (int r = 0; r < 16; ++r) ps += p1[r];
;   { auto rr = __builtin_amdgcn_permlane32_swap(__float_as_uint(ps), __float_as_uint(ps), false, false);
;     ps = __uint_as_float(rr[0]) + __uint_as_float(rr[1]); }
;   l_reg = l_reg * alpha + ps;
; template <typename TQ>
; __device__ __forceinline__ void attn_dense_body(const TQ* __restrict__ Qb, const bf16* __restrict__ Kh, const bf16* __restrict__ Vh,
;                                                 bf16* __restrict__ Ob, int seq, char* lds, const int tid) {
;     ...
;     SBAR(); qkt(pB0, pB1, (bf16*)((char*)K_lds + SHM_K), qr, r32, hi);
;     finishSM(pA0, pA1, alA, l_reg, pa0, pa1, pa2, pa3); SBAR();
;     SLOAD(SO, (j + SDEPTH) * KVBLK); SBAR();
;     pv_d0(o, vb0, pa0, pa1, pa2, pa3); partialSM(pB0, pB1, m_reg, mnB, alB);
.LBB0_1529:
	ds_read_b128 v[64:67], v192 offset:49152
	ds_read_b128 v[68:71], v192 offset:57344
	ds_read_b128 v[208:211], v199 offset:49152
	ds_read_b128 v[212:215], v199 offset:57344
	s_nop 0
	v_add_f32_e32 v160, v162, v161
	s_waitcnt lgkmcnt(3)
	v_mfma_f32_32x32x16_bf16 v[80:95], v[64:67], v[120:123], 0
	v_add_f32_e32 v160, v174, v160
	v_add_f32_e32 v160, v175, v160
	v_add_f32_e32 v160, v204, v160
	v_add_f32_e32 v160, v207, v160
	v_add_f32_e32 v160, v163, v160
	v_add_f32_e32 v160, v173, v160
	v_add_f32_e32 v160, v168, v160
	s_waitcnt lgkmcnt(2)
	v_mfma_f32_32x32x16_bf16 v[64:79], v[68:71], v[120:123], 0
	v_add_f32_e32 v160, v170, v160
	v_add_f32_e32 v160, v171, v160
	v_add_f32_e32 v160, v172, v160
	v_exp_f32_e32 v156, v156
	v_add_f32_e32 v160, v165, v160
	v_exp_f32_e32 v157, v157
	v_add_f32_e32 v160, v166, v160
	s_waitcnt lgkmcnt(1)
	v_mfma_f32_32x32x16_bf16 v[80:95], v[208:211], v[112:115], v[80:95]
	v_exp_f32_e32 v154, v154
	v_add_f32_e32 v160, v167, v160
	v_exp_f32_e32 v155, v155
	v_add_f32_e32 v160, v169, v160
	v_exp_f32_e32 v148, v148
	v_add_f32_e32 v160, v156, v160
	v_exp_f32_e32 v149, v149
	s_waitcnt lgkmcnt(0)
	v_mfma_f32_32x32x16_bf16 v[64:79], v[212:215], v[112:115], v[64:79]
	ds_read_b128 v[208:211], v198 offset:49152
	ds_read_b128 v[212:215], v198 offset:57344
	v_add_f32_e32 v160, v157, v160
	v_exp_f32_e32 v146, v146
	v_add_f32_e32 v160, v154, v160
	v_exp_f32_e32 v147, v147
	v_add_f32_e32 v160, v155, v160
	v_exp_f32_e32 v144, v144
	s_waitcnt lgkmcnt(1)
	v_mfma_f32_32x32x16_bf16 v[80:95], v[208:211], v[124:127], v[80:95]
	v_add_f32_e32 v160, v148, v160
	v_exp_f32_e32 v145, v145
	v_add_f32_e32 v160, v149, v160
	v_exp_f32_e32 v158, v158
	v_add_f32_e32 v160, v146, v160
	v_exp_f32_e32 v159, v159
	v_add_f32_e32 v160, v147, v160
	s_waitcnt lgkmcnt(0)
	v_mfma_f32_32x32x16_bf16 v[64:79], v[212:215], v[124:127], v[64:79]
	ds_read_b128 v[208:211], v195 offset:49152
	ds_read_b128 v[212:215], v195 offset:57344
	v_exp_f32_e32 v152, v152
	v_add_f32_e32 v160, v144, v160
	v_exp_f32_e32 v153, v153
	v_add_f32_e32 v160, v145, v160
	v_exp_f32_e32 v150, v150
	v_add_f32_e32 v160, v158, v160
	s_waitcnt lgkmcnt(1)
	v_mfma_f32_32x32x16_bf16 v[80:95], v[208:211], v[116:119], v[80:95]
	v_exp_f32_e32 v151, v151
	v_add_f32_e32 v160, v159, v160
	v_add_f32_e32 v160, v152, v160
	v_add_f32_e32 v160, v153, v160
	v_add_f32_e32 v160, v150, v160
	v_add_f32_e32 v201, v151, v160
	v_mov_b32_e32 v202, v201
	s_waitcnt lgkmcnt(0)
	v_mfma_f32_32x32x16_bf16 v[64:79], v[212:215], v[116:119], v[64:79]
	ds_read_b128 v[208:211], v194 offset:49152
	ds_read_b128 v[212:215], v194 offset:57344
	v_cvt_pk_bf16_f32 v160, v161, v162
	v_cvt_pk_bf16_f32 v162, v204, v207
	v_permlane32_swap_b32_e32 v201, v202
	v_cvt_pk_bf16_f32 v161, v174, v175
	v_cvt_pk_bf16_f32 v163, v163, v173
	s_waitcnt lgkmcnt(1)
	v_mfma_f32_32x32x16_bf16 v[80:95], v[208:211], v[108:111], v[80:95]
	v_cvt_pk_bf16_f32 v170, v168, v170
	v_cvt_pk_bf16_f32 v171, v171, v172
	v_cvt_pk_bf16_f32 v172, v165, v166
	v_cvt_pk_bf16_f32 v173, v167, v169
	v_cvt_pk_bf16_f32 v166, v156, v157
	s_waitcnt lgkmcnt(0)
	v_mfma_f32_32x32x16_bf16 v[64:79], v[212:215], v[108:111], v[64:79]
	ds_read_b128 v[208:211], v193 offset:49152
	ds_read_b128 v[212:215], v193 offset:57344
	v_cvt_pk_bf16_f32 v167, v154, v155
	v_cvt_pk_bf16_f32 v168, v148, v149
	v_cvt_pk_bf16_f32 v169, v146, v147
	v_cvt_pk_bf16_f32 v204, v144, v145
	v_cvt_pk_bf16_f32 v205, v158, v159
	v_cvt_pk_bf16_f32 v206, v152, v153
	s_waitcnt lgkmcnt(1)
	v_mfma_f32_32x32x16_bf16 v[80:95], v[208:211], v[104:107], v[80:95]
	v_cvt_pk_bf16_f32 v207, v150, v151
	s_waitcnt lgkmcnt(0)
	v_mfma_f32_32x32x16_bf16 v[64:79], v[212:215], v[104:107], v[64:79]
	ds_read_b128 v[208:211], v196 offset:49152
	ds_read_b128 v[212:215], v196 offset:57344
	s_waitcnt lgkmcnt(1)
	v_mfma_f32_32x32x16_bf16 v[80:95], v[208:211], v[100:103], v[80:95]
	s_waitcnt lgkmcnt(0)
	v_mfma_f32_32x32x16_bf16 v[64:79], v[212:215], v[100:103], v[64:79]
	ds_read_b128 v[208:211], v197 offset:49152
	ds_read_b128 v[212:215], v197 offset:57344
	s_waitcnt lgkmcnt(1)
	v_mfma_f32_32x32x16_bf16 v[80:95], v[208:211], v[96:99], v[80:95]
	s_waitcnt lgkmcnt(0)
	v_mfma_f32_32x32x16_bf16 v[64:79], v[212:215], v[96:99], v[64:79]
	s_movk_i32 s4, 0xa000
	v_add_co_u32_e32 v144, vcc, s4, v178
	s_movk_i32 s4, 0xc000
	s_nop 0
	v_addc_co_u32_e32 v145, vcc, -1, v179, vcc
	v_add_co_u32_e32 v148, vcc, s4, v178
	s_mov_b32 s4, 0xe53fa000
	s_nop 0
	v_addc_co_u32_e32 v149, vcc, -1, v179, vcc
	v_add_co_u32_e32 v152, vcc, s4, v178
	s_mov_b32 s4, 0xe53fc000
	s_nop 0
	v_addc_co_u32_e32 v153, vcc, -1, v179, vcc
	v_add_co_u32_e32 v156, vcc, s4, v178
	global_load_dwordx4 v[144:147], v[144:145], off
	s_nop 0
	global_load_dwordx4 v[148:151], v[148:149], off
	v_addc_co_u32_e32 v157, vcc, -1, v179, vcc
	global_load_dwordx4 v[152:155], v[152:153], off
	s_nop 0
	global_load_dwordx4 v[156:159], v[156:157], off
	ds_read_b64_tr_b16 v[208:209], v187 offset:0
	ds_read_b64_tr_b16 v[210:211], v187 offset:0x800
	ds_read_b64_tr_b16 v[212:213], v187 offset:0x1000
	ds_read_b64_tr_b16 v[214:215], v187 offset:0x1800
	ds_read_b64_tr_b16 v[218:219], v187 offset:0x2000
	ds_read_b64_tr_b16 v[220:221], v187 offset:0x2800
	ds_read_b64_tr_b16 v[222:223], v187 offset:0x3000
	ds_read_b64_tr_b16 v[224:225], v187 offset:0x3800
	s_waitcnt lgkmcnt(0)
; #define SWAIT() do { if constexpr (SDEPTH == 2) asm volatile("s_waitcnt vmcnt(4)" ::: "memory"); else asm volatile("s_waitcnt vmcnt(0)" ::: "memory"); } while (0)
; #define RESC(a) do { if (__any((a) < 1.f)) { if (hi == 0) al_l[r32] = (a); asm volatile("s_waitcnt lgkmcnt(0)" ::: "memory"); \
;     for (int d = 0; d < 4; ++d) for (int r = 0; r < 16; ++r) o[d][r] *= al_l[crow(r, hi)]; } } while (0)
; __device__ __forceinline__ void partialSM(f32x16& p0, f32x16& p1, float& m_reg, float& mn, float& alpha) {
;   constexpr float C = SCALE * 1.4426950408889634f;
;   float pmax = p0[0]; for (int r = 1; r < 16; ++r) pmax = fmaxf(pmax, p0[r]); for (int r = 0; r < 16; ++r) pmax = fmaxf(pmax, p1[r]);
;   { auto rr = __builtin_amdgcn_permlane32_swap(__float_as_uint(pmax), __float_as_uint(pmax), false, false);
;     pmax = fmaxf(__uint_as_float(rr[0]), __uint_as_float(rr[1])); }
;   if (__builtin_expect(__all(pmax - m_reg <= THR / SCALE), 1)) { mn = m_reg; alpha = 1.f; }
;   else { mn = fmaxf(m_reg, pmax); alpha = __builtin_amdgcn_exp2f((m_reg - mn) * C); m_reg = mn; }
; template <typename TQ>
; __device__ __forceinline__ void attn_dense_body(const TQ* __restrict__ Qb, const bf16* __restrict__ Kh, const bf16* __restrict__ Vh,
;                                                 bf16* __restrict__ Ob, int seq, char* lds, const int tid) {
;     ...
;     pv_d0(o, vb0, pa0, pa1, pa2, pa3); partialSM(pB0, pB1, m_reg, mnB, alB);
;     __syncthreads(); SWAIT(); SWRITE(0, SE);
;     RESC(alB); __syncthreads();
	s_nop 0
	v_mfma_f32_32x32x16_bf16 v[0:15], v[160:163], v[208:211], v[0:15]
	ds_read_b64_tr_b16 v[208:209], v187 offset:0x200
	ds_read_b64_tr_b16 v[210:211], v187 offset:0xa00
	v_mfma_f32_32x32x16_bf16 v[0:15], v[170:173], v[212:215], v[0:15]
	ds_read_b64_tr_b16 v[212:213], v187 offset:0x1200
	ds_read_b64_tr_b16 v[214:215], v187 offset:0x1a00
	v_mfma_f32_32x32x16_bf16 v[0:15], v[166:169], v[218:221], v[0:15]
	ds_read_b64_tr_b16 v[218:219], v187 offset:0x2200
	ds_read_b64_tr_b16 v[220:221], v187 offset:0x2a00
	v_mfma_f32_32x32x16_bf16 v[0:15], v[204:207], v[222:225], v[0:15]
	ds_read_b64_tr_b16 v[222:223], v187 offset:0x3200
	ds_read_b64_tr_b16 v[224:225], v187 offset:0x3a00
	s_waitcnt lgkmcnt(0)
	v_mfma_f32_32x32x16_bf16 v[48:63], v[160:163], v[208:211], v[48:63]
	ds_read_b64_tr_b16 v[208:209], v187 offset:0x400
	ds_read_b64_tr_b16 v[210:211], v187 offset:0xc00
	v_mfma_f32_32x32x16_bf16 v[48:63], v[170:173], v[212:215], v[48:63]
	ds_read_b64_tr_b16 v[212:213], v187 offset:0x1400
	ds_read_b64_tr_b16 v[214:215], v187 offset:0x1c00
	v_mfma_f32_32x32x16_bf16 v[48:63], v[166:169], v[218:221], v[48:63]
	ds_read_b64_tr_b16 v[218:219], v187 offset:0x2400
	ds_read_b64_tr_b16 v[220:221], v187 offset:0x2c00
	v_mfma_f32_32x32x16_bf16 v[48:63], v[204:207], v[222:225], v[48:63]
	ds_read_b64_tr_b16 v[222:223], v187 offset:0x3400
	ds_read_b64_tr_b16 v[224:225], v187 offset:0x3c00
	s_waitcnt lgkmcnt(0)
	v_mfma_f32_32x32x16_bf16 v[32:47], v[160:163], v[208:211], v[32:47]
	ds_read_b64_tr_b16 v[208:209], v187 offset:0x600
	ds_read_b64_tr_b16 v[210:211], v187 offset:0xe00
	v_mfma_f32_32x32x16_bf16 v[32:47], v[170:173], v[212:215], v[32:47]
	ds_read_b64_tr_b16 v[212:213], v187 offset:0x1600
	ds_read_b64_tr_b16 v[214:215], v187 offset:0x1e00
	v_mfma_f32_32x32x16_bf16 v[32:47], v[166:169], v[218:221], v[32:47]
	ds_read_b64_tr_b16 v[218:219], v187 offset:0x2600
	ds_read_b64_tr_b16 v[220:221], v187 offset:0x2e00
	v_mfma_f32_32x32x16_bf16 v[32:47], v[204:207], v[222:225], v[32:47]
	ds_read_b64_tr_b16 v[222:223], v187 offset:0x3600
	ds_read_b64_tr_b16 v[224:225], v187 offset:0x3e00
	s_waitcnt lgkmcnt(0)
	v_mfma_f32_32x32x16_bf16 v[16:31], v[160:163], v[208:211], v[16:31]
	s_nop 0
	s_nop 0
	v_max_f32_e32 v160, v80, v81
	v_max3_f32 v160, v160, v82, v83
	v_max3_f32 v160, v160, v84, v85
	v_max3_f32 v160, v160, v86, v87
	v_max3_f32 v160, v160, v88, v89
	v_max3_f32 v160, v160, v90, v91
	v_max3_f32 v160, v160, v92, v93
	v_mfma_f32_32x32x16_bf16 v[16:31], v[170:173], v[212:215], v[16:31]
	v_max3_f32 v160, v160, v94, v95
	v_max3_f32 v160, v160, v64, v65
	v_max3_f32 v160, v160, v66, v67
	v_max3_f32 v160, v160, v68, v69
	v_max3_f32 v160, v160, v70, v71
	v_max3_f32 v160, v160, v72, v73
	v_max3_f32 v160, v160, v74, v75
	v_max3_f32 v160, v160, v76, v77
	v_mfma_f32_32x32x16_bf16 v[16:31], v[166:169], v[218:221], v[16:31]
	v_max3_f32 v160, v160, v78, v79
	v_mov_b32_e32 v161, v160
	s_nop 1
	v_permlane32_swap_b32_e32 v160, v161
	s_nop 0
	s_nop 0
	v_max_f32_e32 v160, v160, v161
	v_sub_f32_e32 v161, v160, v164
	v_cmp_ge_f32_e32 vcc, s14, v161
	s_nop 0
	v_max_f32_e32 v160, v164, v160
	v_mfma_f32_32x32x16_bf16 v[16:31], v[204:207], v[222:225], v[16:31]
	v_sub_f32_e32 v161, v164, v160
	v_mul_f32_e32 v161, 0x3e0293ee, v161
	v_exp_f32_e32 v161, v161
	s_cmp_eq_u64 vcc, exec
	s_cselect_b64 s[38:39], -1, 0
	s_barrier
	s_waitcnt vmcnt(4)
	v_cndmask_b32_e64 v203, v161, 1.0, s[38:39]
	v_cmp_gt_f32_e32 vcc, 1.0, v203
	s_waitcnt vmcnt(7)
	ds_write_b128 v188, v[128:131]
	s_waitcnt vmcnt(6)
	ds_write_b128 v189, v[136:139]
	s_waitcnt vmcnt(5)
	ds_write_b128 v190, v[132:135] offset:32768
	s_waitcnt vmcnt(4)
	ds_write_b128 v191, v[140:143] offset:32768
	s_cbranch_vccz .LBB0_1533
	s_and_saveexec_b64 s[4:5], s[36:37]
	ds_write_b32 v184, v203 offset:128
	s_or_b64 exec, exec, s[4:5]
	s_waitcnt lgkmcnt(0)
	v_add_u32_e32 v161, s8, v176
	ds_read_b128 v[166:169], v161 offset:224
	ds_read_b128 v[170:173], v161 offset:192
	ds_read_b128 v[204:207], v161 offset:160
	ds_read_b128 v[208:211], v161 offset:128
	s_waitcnt lgkmcnt(3)
	v_pk_mul_f32 v[12:13], v[12:13], v[166:167]
	s_waitcnt lgkmcnt(2)
	v_pk_mul_f32 v[8:9], v[8:9], v[170:171]
	s_waitcnt lgkmcnt(1)
	v_pk_mul_f32 v[4:5], v[4:5], v[204:205]
	v_pk_mul_f32 v[14:15], v[14:15], v[168:169]
	v_pk_mul_f32 v[10:11], v[10:11], v[172:173]
	v_pk_mul_f32 v[6:7], v[6:7], v[206:207]
	s_waitcnt lgkmcnt(0)
	v_pk_mul_f32 v[2:3], v[2:3], v[210:211]
	v_pk_mul_f32 v[0:1], v[0:1], v[208:209]
	v_pk_mul_f32 v[60:61], v[60:61], v[166:167]
	v_pk_mul_f32 v[56:57], v[56:57], v[170:171]
	v_pk_mul_f32 v[52:53], v[52:53], v[204:205]
	v_pk_mul_f32 v[62:63], v[62:63], v[168:169]
	v_pk_mul_f32 v[58:59], v[58:59], v[172:173]
	v_pk_mul_f32 v[54:55], v[54:55], v[206:207]
	v_pk_mul_f32 v[50:51], v[50:51], v[210:211]
	v_pk_mul_f32 v[48:49], v[48:49], v[208:209]
	v_pk_mul_f32 v[44:45], v[44:45], v[166:167]
	v_pk_mul_f32 v[40:41], v[40:41], v[170:171]
	v_pk_mul_f32 v[36:37], v[36:37], v[204:205]
	v_pk_mul_f32 v[46:47], v[46:47], v[168:169]
	v_pk_mul_f32 v[42:43], v[42:43], v[172:173]
	v_pk_mul_f32 v[38:39], v[38:39], v[206:207]
	v_pk_mul_f32 v[34:35], v[34:35], v[210:211]
	v_pk_mul_f32 v[32:33], v[32:33], v[208:209]
	v_pk_mul_f32 v[28:29], v[28:29], v[166:167]
	v_pk_mul_f32 v[24:25], v[24:25], v[170:171]
	v_pk_mul_f32 v[20:21], v[20:21], v[204:205]
	v_pk_mul_f32 v[30:31], v[30:31], v[168:169]
	v_pk_mul_f32 v[26:27], v[26:27], v[172:173]
	v_pk_mul_f32 v[22:23], v[22:23], v[206:207]
	v_pk_mul_f32 v[18:19], v[18:19], v[210:211]
	v_pk_mul_f32 v[16:17], v[16:17], v[208:209]
; #define SBAR() __builtin_amdgcn_sched_barrier(0)
; #define SLOAD(i, k0) do { sr_[i].vs0 = St::ld8(&Vh[(long)((k0) + sr) * LDK + sc]); sr_[i].vs1 = St::ld8(&Vh[(long)((k0) + 32 + sr) * LDK + sc]); \
;     sr_[i].ks0 = St::ld8(&Kh[(long)((k0) + sr) * LDK + sc]); sr_[i].ks1 = St::ld8(&Kh[(long)((k0) + 32 + sr) * LDK + sc]); } while (0)
; __device__ __forceinline__ void partialSM(f32x16& p0, f32x16& p1, float& m_reg, float& mn, float& alpha) {
;     ...
;   float mnC = -mn * C;
;   for (int r = 0; r < 16; ++r) p0[r] = fmaf(p0[r], C, mnC); for (int r = 0; r < 16; ++r) p1[r] = fmaf(p1[r], C, mnC);
;   for (int r = 0; r < 16; ++r) p0[r] = __builtin_amdgcn_exp2f(p0[r]);
; }
; __device__ __forceinline__ void finishSM(f32x16& p0, f32x16& p1, float alpha, float& l_reg, bf16x8& pa0, bf16x8& pa1, bf16x8& pa2, bf16x8& pa3) {
;   for (int r = 0; r < 16; ++r) p1[r] = __builtin_amdgcn_exp2f(p1[r]);
;   float ps = 0; for (int r = 0; r < 16; ++r) ps += p0[r]; for (int r = 0; r < 16; ++r) ps += p1[r];
;   { auto rr = __builtin_amdgcn_permlane32_swap(__float_as_uint(ps), __float_as_uint(ps), false, false);
;     ps = __uint_as_float(rr[0]) + __uint_as_float(rr[1]); }
;   l_reg = l_reg * alpha + ps;
; template <typename TQ>
; __device__ __forceinline__ void attn_dense_body(const TQ* __restrict__ Qb, const bf16* __restrict__ Kh, const bf16* __restrict__ Vh,
;                                                 bf16* __restrict__ Ob, int seq, char* lds, const int tid) {
;     ...
;     SBAR(); qkt(pA0, pA1, K_lds, qr, r32, hi);
;     finishSM(pB0, pB1, alB, l_reg, pa0, pa1, pa2, pa3); SBAR();
;     if (SDEPTH == 1 || j + 3 < NT) SLOAD(SE, (j + 1 + SDEPTH) * KVBLK); SBAR();
.LBB0_1533:
	v_cndmask_b32_e64 v204, v160, v164, s[38:39]
	v_mul_f32_e32 v205, 0xbe0293ee, v204
	v_fmamk_f32 v80, v80, 0x3e0293ee, v205
	v_fmamk_f32 v81, v81, 0x3e0293ee, v205
	v_fmamk_f32 v82, v82, 0x3e0293ee, v205
	v_fmamk_f32 v83, v83, 0x3e0293ee, v205
	v_fmamk_f32 v84, v84, 0x3e0293ee, v205
	v_fmamk_f32 v85, v85, 0x3e0293ee, v205
	v_fmamk_f32 v86, v86, 0x3e0293ee, v205
	v_fmamk_f32 v87, v87, 0x3e0293ee, v205
	v_fmamk_f32 v88, v88, 0x3e0293ee, v205
	v_fmamk_f32 v89, v89, 0x3e0293ee, v205
	v_fmamk_f32 v90, v90, 0x3e0293ee, v205
	v_fmamk_f32 v91, v91, 0x3e0293ee, v205
	v_fmamk_f32 v92, v92, 0x3e0293ee, v205
	v_fmamk_f32 v93, v93, 0x3e0293ee, v205
	v_fmamk_f32 v94, v94, 0x3e0293ee, v205
	v_fmamk_f32 v95, v95, 0x3e0293ee, v205
	v_exp_f32_e32 v160, v80
	v_exp_f32_e32 v161, v81
	v_exp_f32_e32 v162, v82
	v_exp_f32_e32 v173, v83
	v_exp_f32_e32 v174, v84
	v_exp_f32_e32 v175, v85
	v_exp_f32_e32 v163, v86
	v_exp_f32_e32 v172, v87
	v_exp_f32_e32 v164, v88
	v_exp_f32_e32 v165, v89
	v_exp_f32_e32 v170, v90
	v_exp_f32_e32 v171, v91
	v_exp_f32_e32 v166, v92
	v_exp_f32_e32 v167, v93
	v_exp_f32_e32 v168, v94
	v_exp_f32_e32 v169, v95
	v_fmamk_f32 v214, v64, 0x3e0293ee, v205
	v_fmamk_f32 v215, v65, 0x3e0293ee, v205
	v_fmamk_f32 v217, v66, 0x3e0293ee, v205
	v_fmamk_f32 v218, v67, 0x3e0293ee, v205
	v_fmamk_f32 v219, v68, 0x3e0293ee, v205
	v_fmamk_f32 v207, v69, 0x3e0293ee, v205
	v_fmamk_f32 v208, v70, 0x3e0293ee, v205
	v_fmamk_f32 v209, v71, 0x3e0293ee, v205
	v_fmamk_f32 v210, v72, 0x3e0293ee, v205
	v_fmamk_f32 v211, v73, 0x3e0293ee, v205
	v_fmamk_f32 v212, v74, 0x3e0293ee, v205
	v_fmamk_f32 v213, v75, 0x3e0293ee, v205
	v_fmamk_f32 v206, v76, 0x3e0293ee, v205
	v_fmamk_f32 v220, v77, 0x3e0293ee, v205
	v_fmamk_f32 v221, v78, 0x3e0293ee, v205
	v_fmac_f32_e32 v205, 0x3e0293ee, v79
	s_waitcnt lgkmcnt(0)
	s_barrier
	ds_read_b128 v[64:67], v192 offset:32768
	ds_read_b128 v[68:71], v192 offset:40960
	ds_read_b128 v[222:225], v199 offset:32768
	ds_read_b128 v[226:229], v199 offset:40960
	v_exp_f32_e32 v214, v214
	v_exp_f32_e32 v215, v215
	s_waitcnt lgkmcnt(3)
	v_mfma_f32_32x32x16_bf16 v[80:95], v[64:67], v[120:123], 0
	v_exp_f32_e32 v217, v217
	v_exp_f32_e32 v218, v218
	v_exp_f32_e32 v219, v219
	v_exp_f32_e32 v207, v207
	v_exp_f32_e32 v208, v208
	v_exp_f32_e32 v209, v209
	v_exp_f32_e32 v210, v210
	s_waitcnt lgkmcnt(2)
	v_mfma_f32_32x32x16_bf16 v[64:79], v[68:71], v[120:123], 0
	v_exp_f32_e32 v211, v211
	v_exp_f32_e32 v212, v212
	v_exp_f32_e32 v213, v213
	v_exp_f32_e32 v220, v220
	v_exp_f32_e32 v221, v221
	s_waitcnt lgkmcnt(1)
	v_mfma_f32_32x32x16_bf16 v[80:95], v[222:225], v[112:115], v[80:95]
	s_waitcnt lgkmcnt(0)
	v_mfma_f32_32x32x16_bf16 v[64:79], v[226:229], v[112:115], v[64:79]
	ds_read_b128 v[222:225], v198 offset:32768
	ds_read_b128 v[226:229], v198 offset:40960
	s_waitcnt lgkmcnt(1)
	v_mfma_f32_32x32x16_bf16 v[80:95], v[222:225], v[124:127], v[80:95]
	s_waitcnt lgkmcnt(0)
	v_mfma_f32_32x32x16_bf16 v[64:79], v[226:229], v[124:127], v[64:79]
	ds_read_b128 v[222:225], v195 offset:32768
	ds_read_b128 v[226:229], v195 offset:40960
	s_waitcnt lgkmcnt(1)
	v_mfma_f32_32x32x16_bf16 v[80:95], v[222:225], v[116:119], v[80:95]
	s_waitcnt lgkmcnt(0)
	v_mfma_f32_32x32x16_bf16 v[64:79], v[226:229], v[116:119], v[64:79]
	ds_read_b128 v[222:225], v194 offset:32768
	ds_read_b128 v[226:229], v194 offset:40960
	s_waitcnt lgkmcnt(1)
	v_mfma_f32_32x32x16_bf16 v[80:95], v[222:225], v[108:111], v[80:95]
	s_waitcnt lgkmcnt(0)
	v_mfma_f32_32x32x16_bf16 v[64:79], v[226:229], v[108:111], v[64:79]
	ds_read_b128 v[222:225], v193 offset:32768
	ds_read_b128 v[226:229], v193 offset:40960
	s_waitcnt lgkmcnt(1)
	v_mfma_f32_32x32x16_bf16 v[80:95], v[222:225], v[104:107], v[80:95]
	s_waitcnt lgkmcnt(0)
	v_mfma_f32_32x32x16_bf16 v[64:79], v[226:229], v[104:107], v[64:79]
	ds_read_b128 v[222:225], v196 offset:32768
	ds_read_b128 v[226:229], v196 offset:40960
	s_waitcnt lgkmcnt(1)
	v_mfma_f32_32x32x16_bf16 v[80:95], v[222:225], v[100:103], v[80:95]
	s_waitcnt lgkmcnt(0)
	v_mfma_f32_32x32x16_bf16 v[64:79], v[226:229], v[100:103], v[64:79]
	ds_read_b128 v[222:225], v197 offset:32768
	ds_read_b128 v[226:229], v197 offset:40960
	s_waitcnt lgkmcnt(1)
	v_mfma_f32_32x32x16_bf16 v[80:95], v[222:225], v[96:99], v[80:95]
	v_exp_f32_e32 v223, v205
	s_nop 0
	v_add_f32_e32 v205, v161, v160
	v_add_f32_e32 v205, v162, v205
	v_add_f32_e32 v205, v173, v205
	v_add_f32_e32 v205, v174, v205
	v_add_f32_e32 v205, v175, v205
	v_add_f32_e32 v205, v163, v205
	v_add_f32_e32 v205, v172, v205
	v_add_f32_e32 v205, v164, v205
	v_add_f32_e32 v205, v165, v205
	v_add_f32_e32 v205, v170, v205
	v_add_f32_e32 v205, v171, v205
	v_add_f32_e32 v205, v166, v205
	v_add_f32_e32 v205, v167, v205
	v_add_f32_e32 v205, v168, v205
	v_add_f32_e32 v205, v169, v205
	v_add_f32_e32 v205, v214, v205
	v_add_f32_e32 v205, v215, v205
	v_add_f32_e32 v205, v217, v205
	v_add_f32_e32 v205, v218, v205
	v_add_f32_e32 v205, v219, v205
	v_add_f32_e32 v205, v207, v205
	v_add_f32_e32 v205, v208, v205
	v_add_f32_e32 v205, v209, v205
	v_exp_f32_e32 v222, v206
	v_add_f32_e32 v205, v210, v205
	v_add_f32_e32 v205, v211, v205
	s_waitcnt lgkmcnt(0)
	v_mfma_f32_32x32x16_bf16 v[64:79], v[226:229], v[96:99], v[64:79]
	v_add_f32_e32 v205, v212, v205
	v_add_f32_e32 v205, v213, v205
	v_add_f32_e32 v205, v222, v205
	v_add_f32_e32 v205, v220, v205
	v_add_f32_e32 v205, v221, v205
	v_add_f32_e32 v205, v223, v205
	v_mov_b32_e32 v206, v205
	v_cvt_pk_bf16_f32 v160, v160, v161
	v_cvt_pk_bf16_f32 v161, v162, v173
	v_cvt_pk_bf16_f32 v162, v174, v175
	v_cvt_pk_bf16_f32 v163, v163, v172
	v_cvt_pk_bf16_f32 v164, v164, v165
	v_cvt_pk_bf16_f32 v165, v170, v171
	v_cvt_pk_bf16_f32 v166, v166, v167
	v_cvt_pk_bf16_f32 v167, v168, v169
	v_cvt_pk_bf16_f32 v168, v214, v215
	v_cvt_pk_bf16_f32 v169, v217, v218
	v_cvt_pk_bf16_f32 v170, v219, v207
	v_cvt_pk_bf16_f32 v171, v208, v209
	v_cvt_pk_bf16_f32 v172, v210, v211
	v_cvt_pk_bf16_f32 v173, v212, v213
	v_cvt_pk_bf16_f32 v174, v222, v220
	v_cvt_pk_bf16_f32 v175, v221, v223
	v_permlane32_swap_b32_e32 v205, v206
	s_cmp_gt_u32 s9, 64
	s_cselect_b64 s[4:5], -1, 0
	s_and_b64 vcc, exec, s[4:5]
	s_cbranch_vccnz .LBB0_1535
	v_add_co_u32_e32 v128, vcc, 0xffffe000, v178
	s_nop 1
	v_addc_co_u32_e32 v129, vcc, -1, v179, vcc
	v_add_co_u32_e32 v132, vcc, 0xe53fe000, v178
	s_nop 1
	v_addc_co_u32_e32 v133, vcc, -1, v179, vcc
	v_add_co_u32_e32 v140, vcc, 0xe5400000, v178
	global_load_dwordx4 v[128:131], v[128:129], off
	s_nop 0
	global_load_dwordx4 v[132:135], v[132:133], off
	v_addc_co_u32_e32 v141, vcc, -1, v179, vcc
	global_load_dwordx4 v[136:139], v[178:179], off
	s_nop 0
	global_load_dwordx4 v[140:143], v[140:141], off
; #define SWAIT() do { if constexpr (SDEPTH == 2) asm volatile("s_waitcnt vmcnt(4)" ::: "memory"); else asm volatile("s_waitcnt vmcnt(0)" ::: "memory"); } while (0)
; #define RESC(a) do { if (__any((a) < 1.f)) { if (hi == 0) al_l[r32] = (a); asm volatile("s_waitcnt lgkmcnt(0)" ::: "memory"); \
;     for (int d = 0; d < 4; ++d) for (int r = 0; r < 16; ++r) o[d][r] *= al_l[crow(r, hi)]; } } while (0)
; __device__ __forceinline__ void partialSM(f32x16& p0, f32x16& p1, float& m_reg, float& mn, float& alpha) {
;   constexpr float C = SCALE * 1.4426950408889634f;
;   float pmax = p0[0]; for (int r = 1; r < 16; ++r) pmax = fmaxf(pmax, p0[r]); for (int r = 0; r < 16; ++r) pmax = fmaxf(pmax, p1[r]);
;   { auto rr = __builtin_amdgcn_permlane32_swap(__float_as_uint(pmax), __float_as_uint(pmax), false, false);
;     pmax = fmaxf(__uint_as_float(rr[0]), __uint_as_float(rr[1])); }
;   if (__builtin_expect(__all(pmax - m_reg <= THR / SCALE), 1)) { mn = m_reg; alpha = 1.f; }
;   else { mn = fmaxf(m_reg, pmax); alpha = __builtin_amdgcn_exp2f((m_reg - mn) * C); m_reg = mn; }
; template <typename TQ>
; __device__ __forceinline__ void attn_dense_body(const TQ* __restrict__ Qb, const bf16* __restrict__ Kh, const bf16* __restrict__ Vh,
;                                                 bf16* __restrict__ Ob, int seq, char* lds, const int tid) {
;     ...
;     pv_d0(o, vb0 + (int)SHM_V, pa0, pa1, pa2, pa3); partialSM(pA0, pA1, m_reg, mnA, alA);
;     __syncthreads(); SWAIT(); SWRITE(1, SO);
;     RESC(alA); __syncthreads();
.LBB0_1535:
	ds_read_b64_tr_b16 v[208:209], v186 offset:0
	ds_read_b64_tr_b16 v[210:211], v186 offset:0x800
	ds_read_b64_tr_b16 v[212:213], v186 offset:0x1000
	ds_read_b64_tr_b16 v[214:215], v186 offset:0x1800
	ds_read_b64_tr_b16 v[218:219], v186 offset:0x2000
	ds_read_b64_tr_b16 v[220:221], v186 offset:0x2800
	ds_read_b64_tr_b16 v[222:223], v186 offset:0x3000
	ds_read_b64_tr_b16 v[224:225], v186 offset:0x3800
	s_waitcnt lgkmcnt(0)
	s_nop 0
	v_mfma_f32_32x32x16_bf16 v[0:15], v[160:163], v[208:211], v[0:15]
	ds_read_b64_tr_b16 v[208:209], v186 offset:0x200
	ds_read_b64_tr_b16 v[210:211], v186 offset:0xa00
	v_mfma_f32_32x32x16_bf16 v[0:15], v[164:167], v[212:215], v[0:15]
	ds_read_b64_tr_b16 v[212:213], v186 offset:0x1200
	ds_read_b64_tr_b16 v[214:215], v186 offset:0x1a00
	v_mfma_f32_32x32x16_bf16 v[0:15], v[168:171], v[218:221], v[0:15]
	ds_read_b64_tr_b16 v[218:219], v186 offset:0x2200
	ds_read_b64_tr_b16 v[220:221], v186 offset:0x2a00
	v_mfma_f32_32x32x16_bf16 v[0:15], v[172:175], v[222:225], v[0:15]
	ds_read_b64_tr_b16 v[222:223], v186 offset:0x3200
	ds_read_b64_tr_b16 v[224:225], v186 offset:0x3a00
	s_waitcnt lgkmcnt(0)
	v_mfma_f32_32x32x16_bf16 v[48:63], v[160:163], v[208:211], v[48:63]
	ds_read_b64_tr_b16 v[208:209], v186 offset:0x400
	ds_read_b64_tr_b16 v[210:211], v186 offset:0xc00
	v_mfma_f32_32x32x16_bf16 v[48:63], v[164:167], v[212:215], v[48:63]
	ds_read_b64_tr_b16 v[212:213], v186 offset:0x1400
	ds_read_b64_tr_b16 v[214:215], v186 offset:0x1c00
	v_mfma_f32_32x32x16_bf16 v[48:63], v[168:171], v[218:221], v[48:63]
	ds_read_b64_tr_b16 v[218:219], v186 offset:0x2400
	ds_read_b64_tr_b16 v[220:221], v186 offset:0x2c00
	v_mfma_f32_32x32x16_bf16 v[48:63], v[172:175], v[222:225], v[48:63]
	ds_read_b64_tr_b16 v[222:223], v186 offset:0x3400
	ds_read_b64_tr_b16 v[224:225], v186 offset:0x3c00
	s_waitcnt lgkmcnt(0)
	v_mfma_f32_32x32x16_bf16 v[32:47], v[160:163], v[208:211], v[32:47]
	ds_read_b64_tr_b16 v[208:209], v186 offset:0x600
	ds_read_b64_tr_b16 v[210:211], v186 offset:0xe00
	v_mfma_f32_32x32x16_bf16 v[32:47], v[164:167], v[212:215], v[32:47]
	ds_read_b64_tr_b16 v[212:213], v186 offset:0x1600
	ds_read_b64_tr_b16 v[214:215], v186 offset:0x1e00
	v_mfma_f32_32x32x16_bf16 v[32:47], v[168:171], v[218:221], v[32:47]
	ds_read_b64_tr_b16 v[218:219], v186 offset:0x2600
	ds_read_b64_tr_b16 v[220:221], v186 offset:0x2e00
	v_mfma_f32_32x32x16_bf16 v[32:47], v[172:175], v[222:225], v[32:47]
	ds_read_b64_tr_b16 v[222:223], v186 offset:0x3600
	ds_read_b64_tr_b16 v[224:225], v186 offset:0x3e00
	s_waitcnt lgkmcnt(0)
	v_mfma_f32_32x32x16_bf16 v[16:31], v[160:163], v[208:211], v[16:31]
	s_nop 0
	s_nop 0
	v_max_f32_e32 v160, v80, v81
	v_max3_f32 v160, v160, v82, v83
	v_max3_f32 v160, v160, v84, v85
	v_max3_f32 v160, v160, v86, v87
	v_max3_f32 v160, v160, v88, v89
	v_max3_f32 v160, v160, v90, v91
	v_max3_f32 v160, v160, v92, v93
	v_mfma_f32_32x32x16_bf16 v[16:31], v[164:167], v[212:215], v[16:31]
	v_max3_f32 v160, v160, v94, v95
	v_max3_f32 v160, v160, v64, v65
	v_max3_f32 v160, v160, v66, v67
	v_max3_f32 v160, v160, v68, v69
	v_max3_f32 v160, v160, v70, v71
	v_max3_f32 v160, v160, v72, v73
	v_max3_f32 v160, v160, v74, v75
	v_max3_f32 v160, v160, v76, v77
	v_mfma_f32_32x32x16_bf16 v[16:31], v[168:171], v[218:221], v[16:31]
	v_max3_f32 v160, v160, v78, v79
	v_mov_b32_e32 v161, v160
	s_nop 1
	v_permlane32_swap_b32_e32 v160, v161
	s_nop 0
	s_nop 0
	v_max_f32_e32 v160, v160, v161
	v_sub_f32_e32 v161, v160, v204
	v_cmp_ge_f32_e32 vcc, s14, v161
	s_nop 0
	v_max_f32_e32 v161, v204, v160
	v_mfma_f32_32x32x16_bf16 v[16:31], v[172:175], v[222:225], v[16:31]
	v_sub_f32_e32 v160, v204, v161
	v_mul_f32_e32 v160, 0x3e0293ee, v160
	v_exp_f32_e32 v160, v160
	s_cmp_eq_u64 vcc, exec
	s_cselect_b64 s[38:39], -1, 0
	s_barrier
	s_waitcnt vmcnt(4)
	v_cndmask_b32_e64 v160, v160, 1.0, s[38:39]
	v_cmp_gt_f32_e32 vcc, 1.0, v160
	s_waitcnt vmcnt(3)
	ds_write_b128 v188, v[144:147] offset:16384
	s_waitcnt vmcnt(2)
	ds_write_b128 v189, v[148:151] offset:16384
	s_waitcnt vmcnt(1)
	ds_write_b128 v190, v[152:155] offset:49152
	s_waitcnt vmcnt(0)
	ds_write_b128 v191, v[156:159] offset:49152
	s_cbranch_vccz .LBB0_1539
	s_and_saveexec_b64 s[6:7], s[36:37]
	ds_write_b32 v184, v160 offset:128
	s_or_b64 exec, exec, s[6:7]
	s_waitcnt lgkmcnt(0)
	v_add_u32_e32 v156, s8, v176
	ds_read_b128 v[144:147], v156 offset:224
	ds_read_b128 v[148:151], v156 offset:192
	ds_read_b128 v[152:155], v156 offset:160
	ds_read_b128 v[156:159], v156 offset:128
	s_waitcnt lgkmcnt(3)
	v_pk_mul_f32 v[12:13], v[12:13], v[144:145]
	s_waitcnt lgkmcnt(2)
	v_pk_mul_f32 v[8:9], v[8:9], v[148:149]
	s_waitcnt lgkmcnt(1)
	v_pk_mul_f32 v[4:5], v[4:5], v[152:153]
	v_pk_mul_f32 v[14:15], v[14:15], v[146:147]
	v_pk_mul_f32 v[10:11], v[10:11], v[150:151]
	v_pk_mul_f32 v[6:7], v[6:7], v[154:155]
	s_waitcnt lgkmcnt(0)
	v_pk_mul_f32 v[2:3], v[2:3], v[158:159]
	v_pk_mul_f32 v[0:1], v[0:1], v[156:157]
	v_pk_mul_f32 v[60:61], v[60:61], v[144:145]
	v_pk_mul_f32 v[56:57], v[56:57], v[148:149]
	v_pk_mul_f32 v[52:53], v[52:53], v[152:153]
	v_pk_mul_f32 v[62:63], v[62:63], v[146:147]
	v_pk_mul_f32 v[58:59], v[58:59], v[150:151]
	v_pk_mul_f32 v[54:55], v[54:55], v[154:155]
	v_pk_mul_f32 v[50:51], v[50:51], v[158:159]
	v_pk_mul_f32 v[48:49], v[48:49], v[156:157]
	v_pk_mul_f32 v[44:45], v[44:45], v[144:145]
	v_pk_mul_f32 v[40:41], v[40:41], v[148:149]
	v_pk_mul_f32 v[36:37], v[36:37], v[152:153]
	v_pk_mul_f32 v[46:47], v[46:47], v[146:147]
	v_pk_mul_f32 v[42:43], v[42:43], v[150:151]
	v_pk_mul_f32 v[38:39], v[38:39], v[154:155]
	v_pk_mul_f32 v[34:35], v[34:35], v[158:159]
	v_pk_mul_f32 v[32:33], v[32:33], v[156:157]
	v_pk_mul_f32 v[28:29], v[28:29], v[144:145]
	v_pk_mul_f32 v[24:25], v[24:25], v[148:149]
	v_pk_mul_f32 v[20:21], v[20:21], v[152:153]
	v_pk_mul_f32 v[30:31], v[30:31], v[146:147]
	v_pk_mul_f32 v[26:27], v[26:27], v[150:151]
	v_pk_mul_f32 v[22:23], v[22:23], v[154:155]
	v_pk_mul_f32 v[18:19], v[18:19], v[158:159]
	v_pk_mul_f32 v[16:17], v[16:17], v[156:157]
